# attention tile loop: PV MFMAs accumulate in place, 16 v_mov_b64 + s_nop 7 per tile hoisted out of the loop
# baseline (speedup 1.0000x reference)
; #define LAS __attribute__((address_space(3)))
; __device__ __forceinline__ void attn_phase(LAS unsigned char* lds, const bf16_t* Q, const bf16_t* Kb, const bf16_t* VT, const bf16_t* Zs, bf16_t* OZ, int vcu, int G) {
;     ...
;     for (int unit = vcu; unit < NU; unit += G) {
;         ATT_DECODE(unit, h, rowbase, q0b, kw0)
;         const int qblk = unit & 31;
;         const int qb = 8 * qblk + w, q0 = 32 * qb;
;         bf16x8 qf[4];
;         { const bf16_t* qp = Q + (rowbase + q0 + ql) * D + h * 64 + 8 * hi;
; #pragma unroll
;           for (int kk = 0; kk < 4; ++kk) qf[kk] = *(const bf16x8*)(qp + 16 * kk); }
;         u32x2 zz[8];
;         { const bf16_t* zp = Zs + (rowbase + q0 + ql) * D + h * 64 + 4 * hi;
; #pragma unroll
;           for (int g4 = 0; g4 < 4; ++g4) { zz[g4] = *(const u32x2*)(zp + 8 * g4); zz[4 + g4] = *(const u32x2*)(zp + 32 + 8 * g4); } }
;         asm volatile("" ::: "memory");
; #pragma unroll
;         for (int i = 0; i < 6; ++i) { const int idx = tid + NTHR * i, r = idx >> 3, c = idx & 7;
;             *(LAS u32x4*)(KL + r * 128 + ((c ^ ((r >> 1) & 7)) << 4)) = sk[i]; }
; #pragma unroll
;         for (int i = 0; i < 6; ++i) { const int idx = tid + NTHR * i, d = idx / 48, ch = idx % 48;
;             { u32x4 v = sv[i]; const int gp = (2 * ch) ^ (d & 31);
;                 if (d & 1) { const u32x4 t = v; v.x = t.z; v.y = t.w; v.z = t.x; v.w = t.y; }
;                 *(LAS u32x4*)(VL + d * 768 + ((gp & ~1) << 3)) = v; } }
;         __syncthreads();
;         { const int nu_ = unit + G < NU ? unit + G : unit; ATT_LOAD_STAGE(nu_); }
.LBB0_540:
	s_ashr_i32 s74, s84, 9
	s_ashr_i32 s75, s74, 31
	s_and_b32 s58, s84, 31
	s_lshl_b64 s[78:79], s[74:75], 13
	s_lshl_b32 s74, s58, 3
	s_and_b32 s59, s89, 31
	s_lshl_b32 s81, s58, 8
	s_add_i32 s90, s74, s85
	s_lshl_b32 s91, s59, 3
	s_addk_i32 s81, 0xff80
	s_lshl_b32 s80, s90, 5
	s_add_u32 s74, s78, s80
	s_addc_u32 s75, s79, 0
	v_or_b32_e32 v190, s74, v142
	s_lshl_b32 s74, s84, 1
	s_and_b32 s92, s74, 0x3c0
	s_mov_b32 s72, s84
	s_lshl_b32 s76, s92, 1
	s_add_i32 s84, s84, s3
	v_mov_b32_e32 v191, s75
	s_cmpk_gt_i32 s84, 0x3ff
	v_lshlrev_b64 v[2:3], 11, v[190:191]
	s_cselect_b64 s[74:75], -1, 0
	s_cmpk_lt_i32 s84, 0x400
	v_lshl_add_u64 v[4:5], s[64:65], 0, v[2:3]
	s_mov_b32 s77, s73
	v_lshl_add_u64 v[2:3], s[66:67], 0, v[2:3]
	s_cselect_b32 s72, s84, s72
	v_lshl_add_u64 v[4:5], v[4:5], 0, s[76:77]
	v_lshl_add_u64 v[2:3], v[2:3], 0, s[76:77]
	v_mov_b32_e32 v163, v145
	s_bfe_u32 s77, s72, 0x40005
	s_ashr_i32 s82, s72, 9
	s_lshl_b32 s72, s72, 8
	v_lshl_add_u64 v[4:5], v[4:5], 0, v[144:145]
	v_lshl_add_u64 v[2:3], v[2:3], 0, v[162:163]
	s_ashr_i32 s83, s82, 31
	s_and_b32 s72, s72, 0x1f00
	global_load_dwordx4 v[114:117], v[4:5], off
	global_load_dwordx4 v[118:121], v[4:5], off offset:32
	global_load_dwordx4 v[122:125], v[4:5], off offset:64
	global_load_dwordx4 v[126:129], v[4:5], off offset:96
	global_load_dwordx2 v[192:193], v[2:3], off
	global_load_dwordx2 v[186:187], v[2:3], off offset:16
	global_load_dwordx2 v[182:183], v[2:3], off offset:32
	global_load_dwordx2 v[178:179], v[2:3], off offset:48
	global_load_dwordx2 v[188:189], v[2:3], off offset:64
	global_load_dwordx2 v[184:185], v[2:3], off offset:80
	global_load_dwordx2 v[180:181], v[2:3], off offset:96
	global_load_dwordx2 v[176:177], v[2:3], off offset:112
	s_waitcnt vmcnt(17)
	v_cndmask_b32_e64 v5, v95, v97, s[48:49]
	v_cndmask_b32_e64 v4, v94, v96, s[48:49]
	v_cndmask_b32_e64 v3, v97, v95, s[48:49]
	v_cndmask_b32_e64 v2, v96, v94, s[48:49]
	s_lshl_b64 s[94:95], s[82:83], 13
	s_add_i32 s93, s72, 0xffffff80
	ds_write_b128 v206, v[66:69]
	ds_write_b128 v207, v[70:73]
	ds_write_b128 v206, v[74:77] offset:16384
	ds_write_b128 v208, v[78:81]
	ds_write_b128 v206, v[82:85] offset:32768
	ds_write_b128 v209, v[86:89]
	ds_write_b128 v210, v[2:5] offset:49152
	s_waitcnt vmcnt(16)
	v_cndmask_b32_e64 v5, v91, v93, s[4:5]
	v_cndmask_b32_e64 v4, v90, v92, s[4:5]
	v_cndmask_b32_e64 v3, v93, v91, s[4:5]
	v_cndmask_b32_e64 v2, v92, v90, s[4:5]
	s_cmp_lg_u32 s72, 0
	ds_write_b128 v211, v[2:5] offset:49152
	s_waitcnt vmcnt(15)
	v_cndmask_b32_e64 v5, v103, v105, s[6:7]
	v_cndmask_b32_e64 v4, v102, v104, s[6:7]
	v_cndmask_b32_e64 v3, v105, v103, s[6:7]
	v_cndmask_b32_e64 v2, v104, v102, s[6:7]
	s_cselect_b32 s96, s93, 0
	ds_write_b128 v212, v[2:5] offset:49152
	s_waitcnt vmcnt(14)
	v_cndmask_b32_e64 v5, v99, v101, s[8:9]
	v_cndmask_b32_e64 v4, v98, v100, s[8:9]
	v_cndmask_b32_e64 v3, v101, v99, s[8:9]
	v_cndmask_b32_e64 v2, v100, v98, s[8:9]
	s_ashr_i32 s97, s96, 31
	ds_write_b128 v213, v[2:5] offset:49152
	s_waitcnt vmcnt(13)
	v_cndmask_b32_e64 v5, v111, v113, s[10:11]
	v_cndmask_b32_e64 v4, v110, v112, s[10:11]
	v_cndmask_b32_e64 v3, v113, v111, s[10:11]
	v_cndmask_b32_e64 v2, v112, v110, s[10:11]
	s_add_u32 s94, s94, s96
	ds_write_b128 v214, v[2:5] offset:49152
	s_waitcnt vmcnt(12)
	v_cndmask_b32_e64 v5, v107, v109, s[12:13]
	v_cndmask_b32_e64 v4, v106, v108, s[12:13]
	v_cndmask_b32_e64 v3, v109, v107, s[12:13]
	v_cndmask_b32_e64 v2, v108, v106, s[12:13]
	s_addc_u32 s95, s95, s97
	ds_write_b128 v215, v[2:5] offset:49152
	s_lshl_b32 s72, s77, 7
	v_mov_b32_e32 v5, s95
	v_or_b32_e32 v4, s94, v146
	v_mov_b32_e32 v7, s95
	v_or_b32_e32 v6, s94, v148
	v_lshl_add_u64 v[2:3], v[158:159], 0, s[72:73]
	v_lshlrev_b64 v[4:5], 11, v[4:5]
	v_lshlrev_b64 v[6:7], 11, v[6:7]
	v_lshl_add_u64 v[4:5], v[2:3], 0, v[4:5]
	v_lshl_add_u64 v[6:7], v[2:3], 0, v[6:7]
	s_waitcnt lgkmcnt(0)
	s_barrier
	global_load_dwordx4 v[66:69], v[4:5], off
	global_load_dwordx4 v[70:73], v[6:7], off
	v_lshl_add_u64 v[4:5], s[94:95], 0, v[150:151]
	v_lshl_add_u64 v[6:7], s[94:95], 0, v[152:153]
	v_lshlrev_b64 v[4:5], 11, v[4:5]
	v_lshlrev_b64 v[6:7], 11, v[6:7]
	v_lshl_add_u64 v[4:5], v[2:3], 0, v[4:5]
	v_lshl_add_u64 v[6:7], v[2:3], 0, v[6:7]
	global_load_dwordx4 v[74:77], v[4:5], off
	global_load_dwordx4 v[78:81], v[6:7], off
	v_lshl_add_u64 v[4:5], s[94:95], 0, v[154:155]
	v_lshl_add_u64 v[6:7], s[94:95], 0, v[156:157]
	s_lshl_b32 s72, s77, 20
	s_lshl_b64 s[82:83], s[82:83], 14
	v_lshlrev_b64 v[4:5], 11, v[4:5]
	v_lshlrev_b64 v[6:7], 11, v[6:7]
	s_add_u32 s77, s68, s82
	v_lshl_add_u64 v[4:5], v[2:3], 0, v[4:5]
	v_lshl_add_u64 v[2:3], v[2:3], 0, v[6:7]
	s_addc_u32 s93, s69, s83
	s_lshl_b64 s[82:83], s[96:97], 1
	global_load_dwordx4 v[82:85], v[4:5], off
	global_load_dwordx4 v[86:89], v[2:3], off
	s_add_u32 s82, s77, s82
	v_or_b32_e32 v2, s72, v196
	s_addc_u32 s83, s93, s83
	v_lshlrev_b32_e32 v2, 1, v2
	v_mov_b32_e32 v3, v145
	v_or_b32_e32 v4, s72, v197
	v_lshl_add_u64 v[2:3], s[82:83], 0, v[2:3]
	v_mov_b32_e32 v165, v145
	v_lshlrev_b32_e32 v4, 1, v4
	v_mov_b32_e32 v5, v145
	v_lshl_add_u64 v[2:3], v[2:3], 0, v[164:165]
	v_lshl_add_u64 v[4:5], s[82:83], 0, v[4:5]
	v_mov_b32_e32 v167, v145
	v_lshl_add_u64 v[4:5], v[4:5], 0, v[166:167]
	global_load_dwordx4 v[94:97], v[2:3], off
	global_load_dwordx4 v[90:93], v[4:5], off
	v_or_b32_e32 v2, s72, v198
	v_lshlrev_b32_e32 v2, 1, v2
	v_mov_b32_e32 v3, v145
	v_or_b32_e32 v4, s72, v199
	v_lshl_add_u64 v[2:3], s[82:83], 0, v[2:3]
	v_mov_b32_e32 v169, v145
	v_lshlrev_b32_e32 v4, 1, v4
	v_mov_b32_e32 v5, v145
	v_lshl_add_u64 v[2:3], v[2:3], 0, v[168:169]
	v_lshl_add_u64 v[4:5], s[82:83], 0, v[4:5]
	v_mov_b32_e32 v171, v145
	v_lshl_add_u64 v[4:5], v[4:5], 0, v[170:171]
	global_load_dwordx4 v[102:105], v[2:3], off
	global_load_dwordx4 v[98:101], v[4:5], off
	v_or_b32_e32 v2, s72, v200
	v_lshlrev_b32_e32 v2, 1, v2
	v_mov_b32_e32 v3, v145
	v_or_b32_e32 v4, s72, v201
	v_lshl_add_u64 v[2:3], s[82:83], 0, v[2:3]
	v_mov_b32_e32 v173, v145
	v_lshlrev_b32_e32 v4, 1, v4
	v_mov_b32_e32 v5, v145
	v_lshl_add_u64 v[2:3], v[2:3], 0, v[172:173]
	v_lshl_add_u64 v[4:5], s[82:83], 0, v[4:5]
	v_mov_b32_e32 v175, v145
	v_lshl_add_u64 v[4:5], v[4:5], 0, v[174:175]
	global_load_dwordx4 v[110:113], v[2:3], off
	global_load_dwordx4 v[106:109], v[4:5], off
	s_cmp_lg_u32 s58, 0
	s_cselect_b32 s58, s81, 0
	s_cmp_lt_i32 s80, s58
	s_cbranch_scc1 .LBB0_552
	s_sub_i32 s72, s80, s58
	v_or_b32_e32 v2, s72, v142
	v_lshrrev_b32_e32 v27, 1, v2
	v_lshl_add_u32 v26, v2, 7, 0
	v_bitop3_b32 v2, v27, v1, 7 bitop3:0x6c
	v_lshl_add_u32 v2, v2, 4, v26
	ds_read_b128 v[2:5], v2
	s_lshr_b32 s77, s72, 2
	v_bitop3_b32 v6, s77, v142, v1 bitop3:0x36
	v_lshlrev_b32_e32 v30, 3, v6
	v_bitop3_b32 v6, v27, v143, 7 bitop3:0x6c
	v_lshl_add_u32 v6, v6, 4, v26
	ds_read_b128 v[18:21], v6
	v_or_b32_e32 v28, s77, v1
	s_waitcnt vmcnt(23) lgkmcnt(1)
	v_mfma_f32_32x32x16_bf16 v[2:17], v[2:5], v[114:117], 0
	v_bitop3_b32 v22, v28, v142, 2 bitop3:0x36
	v_lshlrev_b32_e32 v32, 3, v22
	v_bitop3_b32 v22, v28, v142, 4 bitop3:0x36
	v_lshlrev_b32_e32 v38, 3, v22
	v_bitop3_b32 v22, v27, v147, 7 bitop3:0x6c
	v_lshl_add_u32 v22, v22, 4, v26
	ds_read_b128 v[22:25], v22
	s_waitcnt vmcnt(22) lgkmcnt(1)
	v_mfma_f32_32x32x16_bf16 v[2:17], v[18:21], v[118:121], v[2:17]
	v_bitop3_b32 v18, v28, v142, 6 bitop3:0x36
	v_lshlrev_b32_e32 v39, 3, v18
	v_bitop3_b32 v18, v27, v149, 7 bitop3:0x6c
	v_lshl_add_u32 v18, v18, 4, v26
	ds_read_b128 v[26:29], v18
	v_add_u32_e32 v31, v202, v30
	v_add_u32_e32 v34, v202, v38
	s_waitcnt vmcnt(21) lgkmcnt(1)
	v_mfma_f32_32x32x16_bf16 v[2:17], v[22:25], v[122:125], v[2:17]
	v_add_u32_e32 v36, v202, v39
	v_add_u32_e32 v22, v203, v30
	v_add_u32_e32 v24, v203, v38
	v_add_u32_e32 v33, v202, v32
	ds_read_b64 v[18:19], v31 offset:49152
	ds_read_b64 v[20:21], v33 offset:49152
	ds_read_b64 v[34:35], v34 offset:49152
	ds_read_b64 v[36:37], v36 offset:49152
	v_add_u32_e32 v23, v203, v32
	v_add_u32_e32 v25, v203, v39
	s_waitcnt vmcnt(20) lgkmcnt(4)
	v_mfma_f32_32x32x16_bf16 v[2:17], v[26:29], v[126:129], v[2:17]
	ds_read_b64 v[42:43], v22 offset:24576
	ds_read_b64 v[44:45], v23 offset:24576
	ds_read_b64 v[38:39], v24 offset:24576
	ds_read_b64 v[40:41], v25 offset:24576
	v_and_b32_e32 v48, 64, v216
	v_add_u32_e32 v48, 64, v48
	s_mov_b64 s[80:81], 0
	s_nop 4
	v_min_f32_e64 v3, -v3, s98
	v_exp_f32_e32 v3, v3
	v_min_f32_e64 v4, -v4, s98
	v_exp_f32_e32 v24, v4
	v_add_f32_e32 v22, 1.0, v3
	v_min_f32_e64 v4, -v5, s98
	v_rcp_f32_e32 v22, v22
	v_exp_f32_e32 v5, v4
	v_add_f32_e32 v4, 1.0, v24
	v_mul_f32_e32 v3, v3, v22
	v_rcp_f32_e32 v25, v4
	v_cndmask_b32_e64 v4, 1.0, v3, s[16:17]
	v_add_f32_e32 v3, 1.0, v5
	v_min_f32_e64 v2, -v2, s98
	v_rcp_f32_e32 v3, v3
	v_exp_f32_e32 v2, v2
	v_mul_f32_e32 v24, v24, v25
	v_cndmask_b32_e64 v46, 1.0, v24, s[18:19]
	v_mul_f32_e32 v5, v5, v3
	v_cndmask_b32_e64 v24, 0, v3, s[20:21]
	v_min_f32_e64 v3, -v6, s98
	v_min_f32_e64 v6, -v7, s98
	v_add_f32_e32 v26, 1.0, v2
	v_exp_f32_e32 v3, v3
	v_rcp_f32_e32 v26, v26
	v_exp_f32_e32 v7, v6
	v_add_f32_e32 v6, 1.0, v3
	v_cndmask_b32_e64 v22, 0, v22, s[16:17]
	v_mul_f32_e32 v2, v2, v26
	v_cndmask_b32_e64 v23, 0, v26, s[14:15]
	v_rcp_f32_e32 v26, v6
	v_cndmask_b32_e64 v6, 1.0, v5, s[20:21]
	v_add_f32_e32 v5, 1.0, v7
	v_rcp_f32_e32 v5, v5
	v_mul_f32_e32 v3, v3, v26
	v_cndmask_b32_e64 v3, 1.0, v3, s[22:23]
	v_cndmask_b32_e64 v2, 1.0, v2, s[14:15]
	v_mul_f32_e32 v7, v7, v5
	v_cndmask_b32_e64 v27, 0, v5, s[24:25]
	v_min_f32_e64 v5, -v8, s98
	v_min_f32_e64 v8, -v9, s98
	v_exp_f32_e32 v5, v5
	v_exp_f32_e32 v8, v8
	v_cndmask_b32_e64 v28, 1.0, v7, s[24:25]
	v_add_f32_e32 v9, 1.0, v5
	v_rcp_f32_e32 v9, v9
	v_add_f32_e32 v7, 1.0, v8
	v_rcp_f32_e32 v7, v7
	v_mul_f32_e32 v3, v3, v28
	v_mul_f32_e32 v5, v5, v9
	v_cndmask_b32_e64 v30, 1.0, v5, s[26:27]
	v_mul_f32_e32 v5, v8, v7
	v_min_f32_e64 v8, -v11, s98
	v_cndmask_b32_e64 v31, 0, v7, s[28:29]
	v_min_f32_e64 v7, -v10, s98
	v_exp_f32_e32 v8, v8
	v_exp_f32_e32 v7, v7
	v_cndmask_b32_e64 v10, 1.0, v5, s[28:29]
	v_cndmask_b32_e64 v29, 0, v9, s[26:27]
	v_add_f32_e32 v5, 1.0, v8
	v_add_f32_e32 v9, 1.0, v7
	v_rcp_f32_e32 v5, v5
	v_rcp_f32_e32 v9, v9
	v_cndmask_b32_e64 v25, 0, v25, s[18:19]
	v_cndmask_b32_e64 v26, 0, v26, s[22:23]
	v_mul_f32_e32 v8, v8, v5
	v_cndmask_b32_e64 v51, 0, v5, s[34:35]
	v_min_f32_e64 v5, -v12, s98
	v_mul_f32_e32 v7, v7, v9
	v_cndmask_b32_e64 v50, 0, v9, s[30:31]
	v_min_f32_e64 v9, -v13, s98
	v_exp_f32_e32 v5, v5
	v_exp_f32_e32 v9, v9
	v_cndmask_b32_e64 v12, 1.0, v8, s[34:35]
	v_add_f32_e32 v11, 1.0, v5
	v_rcp_f32_e32 v11, v11
	v_add_f32_e32 v8, 1.0, v9
	v_rcp_f32_e32 v8, v8
	v_cndmask_b32_e64 v7, 1.0, v7, s[30:31]
	v_mul_f32_e32 v5, v5, v11
	v_cndmask_b32_e64 v52, 0, v11, s[36:37]
	v_cndmask_b32_e64 v11, 1.0, v5, s[36:37]
	v_mul_f32_e32 v5, v9, v8
	v_min_f32_e64 v9, -v15, s98
	v_exp_f32_e32 v9, v9
	v_cndmask_b32_e64 v15, 1.0, v5, s[38:39]
	v_cndmask_b32_e64 v13, 0, v8, s[38:39]
	v_min_f32_e64 v8, -v14, s98
	v_add_f32_e32 v5, 1.0, v9
	v_rcp_f32_e32 v5, v5
	v_exp_f32_e32 v8, v8
	v_mul_f32_e32 v7, v7, v12
	v_mul_f32_e32 v9, v9, v5
	v_cndmask_b32_e64 v32, 0, v5, s[42:43]
	v_min_f32_e64 v5, -v16, s98
	v_min_f32_e64 v16, -v17, s98
	v_exp_f32_e32 v5, v5
	v_exp_f32_e32 v16, v16
	v_add_f32_e32 v14, 1.0, v8
	v_add_f32_e32 v17, 1.0, v5
	v_rcp_f32_e32 v17, v17
	v_add_f32_e32 v33, 1.0, v16
	v_rcp_f32_e32 v33, v33
	v_rcp_f32_e32 v14, v14
	v_mul_f32_e32 v5, v5, v17
	v_cndmask_b32_e64 v47, 1.0, v5, s[44:45]
	v_mul_f32_e32 v5, v16, v33
	v_mul_f32_e32 v8, v8, v14
	v_cndmask_b32_e64 v16, 0, v33, s[46:47]
	v_cndmask_b32_e64 v33, 1.0, v5, s[46:47]
	v_xor_b32_e32 v5, 32, v216
	v_cndmask_b32_e64 v8, 1.0, v8, s[40:41]
	v_cndmask_b32_e64 v9, 1.0, v9, s[42:43]
	v_cmp_lt_i32_e32 vcc, v5, v48
	v_mul_f32_e32 v8, v8, v9
	v_mul_f32_e32 v48, v47, v33
	v_cndmask_b32_e32 v5, v216, v5, vcc
	v_lshlrev_b32_e32 v163, 2, v5
	v_mul_f32_e32 v8, v8, v48
	ds_bpermute_b32 v48, v163, v8
	v_mul_f32_e32 v49, v11, v15
	v_mul_f32_e32 v5, v30, v10
	v_mul_f32_e32 v7, v7, v49
	v_mul_f32_e32 v3, v3, v5
	ds_bpermute_b32 v53, v163, v7
	ds_bpermute_b32 v5, v163, v3
	s_waitcnt lgkmcnt(2)
; __device__ __forceinline__ void attn_phase(LAS unsigned char* lds, const bf16_t* Q, const bf16_t* Kb, const bf16_t* VT, const bf16_t* Zs, bf16_t* OZ, int vcu, int G) {
;     ...
;         int kt = qb; bool done = false;
;     ...
;             ATT_TILE(true)
;             if (__all(carry < STOP)) { done = true; break; }
;         }
	v_cndmask_b32_e64 v49, 1.0, v48, s[0:1]
	v_mul_f32_e32 v33, v33, v49
	v_mul_f32_e32 v47, v47, v33
	v_mul_f32_e32 v54, v9, v47
	v_mul_f32_e32 v57, v32, v47
	v_mul_f32_e32 v47, v8, v48
	s_waitcnt lgkmcnt(1)
	v_mul_f32_e32 v7, v7, v53
	v_pk_mul_f32 v[8:9], v[46:47], v[6:7]
	s_waitcnt lgkmcnt(0)
	v_pk_mul_f32 v[2:3], v[2:3], v[4:5]
	v_mul_f32_e32 v55, v16, v49
	v_pk_mul_f32 v[48:49], v[2:3], v[8:9]
	ds_bpermute_b32 v58, v163, v48
	v_mul_f32_e32 v2, v9, v5
	v_cndmask_b32_e64 v2, v9, v2, s[0:1]
	v_mul_f32_e32 v3, v10, v2
	v_mul_f32_e32 v8, v31, v2
	s_waitcnt lgkmcnt(0)
	v_mul_f32_e32 v2, v49, v58
	v_cndmask_b32_e64 v2, v49, v2, s[0:1]
	v_mul_f32_e32 v5, v30, v3
	v_mul_f32_e32 v9, v29, v3
	v_mul_f32_e32 v3, v6, v2
	v_mul_f32_e32 v6, v46, v3
	v_mul_f32_e32 v4, v4, v6
	v_mul_f32_e32 v10, v24, v2
	v_mul_f32_e32 v2, v22, v6
	v_mul_f32_e32 v6, v47, v53
	v_mul_f32_e32 v7, v28, v5
	v_cndmask_b32_e64 v6, v47, v6, s[0:1]
	v_mul_f32_e32 v5, v27, v5
	v_mul_f32_e32 v7, v26, v7
	v_mul_f32_e32 v3, v25, v3
	v_mul_f32_e32 v4, v23, v4
	v_mul_f32_e32 v47, v15, v6
	v_cndmask_b32_e64 v14, 0, v14, s[40:41]
	v_cndmask_b32_e64 v17, 0, v17, s[44:45]
	v_cvt_pk_bf16_f32 v2, v4, v2
	v_cvt_pk_bf16_f32 v3, v3, v10
	v_cvt_pk_bf16_f32 v4, v7, v5
	v_cvt_pk_bf16_f32 v5, v9, v8
	v_mul_f32_e32 v53, v11, v47
	v_mul_f32_e32 v56, v17, v33
	v_mfma_f32_32x32x16_bf16 v[18:33], v[18:21], v[2:5], 0
	v_mul_f32_e32 v46, v14, v54
	v_mul_f32_e32 v54, v12, v53
	v_mul_f32_e32 v59, v13, v6
	v_mfma_f32_32x32x16_bf16 v[2:17], v[42:45], v[2:5], 0
	v_mul_f32_e32 v43, v52, v47
	v_mul_f32_e32 v42, v51, v53
	v_mul_f32_e32 v44, v50, v54
	v_cvt_pk_bf16_f32 v42, v44, v42
	v_cvt_pk_bf16_f32 v43, v43, v59
	v_cvt_pk_bf16_f32 v44, v46, v57
	v_cvt_pk_bf16_f32 v45, v56, v55
	s_nop 1
	v_mfma_f32_32x32x16_bf16 v[18:33], v[34:37], v[42:45], v[18:33]
	v_mul_f32_e32 v34, v48, v58
	v_mul_f32_e32 v131, v34, v49
	v_cmp_gt_f32_e32 vcc, s88, v131
	s_cmp_eq_u64 vcc, exec
	v_mfma_f32_32x32x16_bf16 v[2:17], v[38:41], v[42:45], v[2:17]
	s_cbranch_scc1 .LBB0_553
	s_cmp_eq_u32 s90, 0
	s_cbranch_scc1 .LBB0_556
	s_lshl_b32 s72, s59, 8
	s_lshl_b32 s77, s59, 15
	s_sub_i32 s59, s72, 32
	v_add_u32_e32 v34, s72, v204
	s_lshl_b32 s72, s58, 7
	s_sub_i32 s72, s77, s72
	s_add_i32 s93, s86, s91
	v_subrev_u32_e32 v165, s58, v34
	v_add_u32_e32 v167, s72, v205
	s_sub_i32 s77, s59, s58
	s_nop 7
	v_mov_b64_e32 v[34:35], v[2:3]
	v_mov_b64_e32 v[36:37], v[4:5]
	v_mov_b64_e32 v[38:39], v[6:7]
	v_mov_b64_e32 v[40:41], v[8:9]
	v_mov_b64_e32 v[42:43], v[10:11]
	v_mov_b64_e32 v[44:45], v[12:13]
	v_mov_b64_e32 v[46:47], v[14:15]
	v_mov_b64_e32 v[48:49], v[16:17]
	v_mov_b64_e32 v[50:51], v[18:19]
	v_mov_b64_e32 v[52:53], v[20:21]
	v_mov_b64_e32 v[54:55], v[22:23]
	v_mov_b64_e32 v[56:57], v[24:25]
	v_mov_b64_e32 v[58:59], v[26:27]
	v_mov_b64_e32 v[60:61], v[28:29]
	v_mov_b64_e32 v[62:63], v[30:31]
	v_mov_b64_e32 v[64:65], v[32:33]
	s_branch .LBB0_545

; __device__ __forceinline__ void attn_phase(LAS unsigned char* lds, const bf16_t* Q, const bf16_t* Kb, const bf16_t* VT, const bf16_t* Zs, bf16_t* OZ, int vcu, int G) {
;     ...
;         int kt = qb; bool done = false;
;     ...
;             ATT_TILE(true)
.LBB0_545:
	s_add_i32 s72, s87, s59
	v_mov_b32_e32 v195, v131
	s_cmp_lt_i32 s72, s58
	s_mov_b32 s72, s93
	s_cbranch_scc1 .LBB0_544
	v_add_u32_e32 v2, s87, v165
	v_lshrrev_b32_e32 v26, 1, v2
	v_bitop3_b32 v2, v26, v1, 7 bitop3:0x6c
	v_lshl_add_u32 v2, v2, 4, v167
	ds_read_b128 v[2:5], v2
	s_add_i32 s80, s87, s77
	s_lshr_b32 s80, s80, 2
	v_bitop3_b32 v6, s80, v142, v1 bitop3:0x36
	v_lshlrev_b32_e32 v28, 3, v6
	v_bitop3_b32 v6, v26, v143, 7 bitop3:0x6c
	v_lshl_add_u32 v6, v6, 4, v167
	ds_read_b128 v[18:21], v6
	v_or_b32_e32 v27, s80, v1
	s_waitcnt lgkmcnt(1)
	v_mfma_f32_32x32x16_bf16 v[2:17], v[2:5], v[114:117], 0
	v_bitop3_b32 v22, v27, v142, 2 bitop3:0x36
	v_lshlrev_b32_e32 v30, 3, v22
	v_bitop3_b32 v22, v27, v142, 4 bitop3:0x36
	v_lshlrev_b32_e32 v32, 3, v22
	v_bitop3_b32 v22, v26, v147, 7 bitop3:0x6c
	v_lshl_add_u32 v22, v22, 4, v167
	ds_read_b128 v[22:25], v22
	s_waitcnt lgkmcnt(1)
	v_mfma_f32_32x32x16_bf16 v[2:17], v[18:21], v[118:121], v[2:17]
	v_bitop3_b32 v18, v27, v142, 6 bitop3:0x36
	v_lshlrev_b32_e32 v27, 3, v18
	v_bitop3_b32 v18, v26, v149, 7 bitop3:0x6c
	v_lshl_add_u32 v18, v18, 4, v167
	ds_read_b128 v[18:21], v18
	v_add_u32_e32 v29, v202, v28
	v_add_u32_e32 v132, v202, v27
	s_waitcnt lgkmcnt(1)
	v_mfma_f32_32x32x16_bf16 v[2:17], v[22:25], v[122:125], v[2:17]
	v_add_u32_e32 v22, v203, v28
	v_add_u32_e32 v31, v202, v30
	v_add_u32_e32 v33, v202, v32
	ds_read_b64 v[138:139], v29 offset:49152
	ds_read_b64 v[140:141], v31 offset:49152
	ds_read_b64 v[130:131], v33 offset:49152
	ds_read_b64 v[132:133], v132 offset:49152
	v_add_u32_e32 v23, v203, v30
	v_add_u32_e32 v24, v203, v32
	v_add_u32_e32 v25, v203, v27
	s_waitcnt lgkmcnt(4)
	v_mfma_f32_32x32x16_bf16 v[2:17], v[18:21], v[126:129], v[2:17]
	ds_read_b64 v[218:219], v22 offset:24576
	ds_read_b64 v[220:221], v23 offset:24576
	ds_read_b64 v[134:135], v24 offset:24576
	ds_read_b64 v[136:137], v25 offset:24576
	s_add_i32 s90, s90, -1
	s_nop 6
	v_min_f32_e64 v3, -v3, s98
	v_exp_f32_e32 v3, v3
	v_min_f32_e64 v5, -v5, s98
	v_min_f32_e64 v4, -v4, s98
	v_add_f32_e32 v19, 1.0, v3
	v_exp_f32_e32 v194, v5
	v_min_f32_e64 v5, -v6, s98
	v_rcp_f32_e32 v169, v19
	v_exp_f32_e32 v4, v4
	v_exp_f32_e32 v6, v5
	v_min_f32_e64 v5, -v7, s98
	v_exp_f32_e32 v7, v5
	v_mul_f32_e32 v20, v3, v169
	v_add_f32_e32 v3, 1.0, v4
	v_rcp_f32_e32 v22, v3
	v_add_f32_e32 v3, 1.0, v194
	v_rcp_f32_e32 v24, v3
	v_add_f32_e32 v3, 1.0, v6
	v_rcp_f32_e32 v26, v3
	v_add_f32_e32 v3, 1.0, v7
	v_rcp_f32_e32 v27, v3
	v_min_f32_e64 v3, -v8, s98
	v_exp_f32_e32 v8, v3
	v_min_f32_e64 v3, -v9, s98
	v_exp_f32_e32 v9, v3
	v_add_f32_e32 v3, 1.0, v8
	v_rcp_f32_e32 v28, v3
	v_min_f32_e64 v5, -v12, s98
	v_add_f32_e32 v3, 1.0, v9
	v_rcp_f32_e32 v29, v3
	v_min_f32_e64 v3, -v10, s98
	v_exp_f32_e32 v10, v3
	v_min_f32_e64 v3, -v11, s98
	v_exp_f32_e32 v11, v5
	v_min_f32_e64 v5, -v13, s98
	v_exp_f32_e32 v31, v5
	v_min_f32_e64 v5, -v14, s98
	v_exp_f32_e32 v30, v3
	v_exp_f32_e32 v12, v5
	v_min_f32_e64 v5, -v15, s98
	v_exp_f32_e32 v14, v5
	v_min_f32_e64 v5, -v16, s98
	v_add_f32_e32 v3, 1.0, v10
	v_rcp_f32_e32 v226, v3
	v_add_f32_e32 v3, 1.0, v30
	v_exp_f32_e32 v13, v5
	v_min_f32_e64 v5, -v17, s98
	v_rcp_f32_e32 v228, v3
	v_add_f32_e32 v3, 1.0, v11
	v_rcp_f32_e32 v227, v3
	v_add_f32_e32 v3, 1.0, v31
	v_exp_f32_e32 v15, v5
	v_rcp_f32_e32 v229, v3
	v_add_f32_e32 v3, 1.0, v12
	v_rcp_f32_e32 v230, v3
	v_add_f32_e32 v3, 1.0, v14
	v_rcp_f32_e32 v16, v3
	v_add_f32_e32 v3, 1.0, v13
	v_rcp_f32_e32 v231, v3
	v_add_f32_e32 v3, 1.0, v15
	v_rcp_f32_e32 v17, v3
	v_min_f32_e64 v2, -v2, s98
	v_exp_f32_e32 v2, v2
	v_pk_mul_f32 v[12:13], v[12:13], v[230:231]
	v_pk_mul_f32 v[14:15], v[14:15], v[16:17]
	v_pk_mul_f32 v[6:7], v[6:7], v[26:27]
	v_pk_mul_f32 v[224:225], v[12:13], v[14:15]
	v_add_f32_e32 v18, 1.0, v2
	v_mul_f32_e32 v3, v224, v225
	ds_bpermute_b32 v5, v163, v3
	v_rcp_f32_e32 v18, v18
	v_pk_mul_f32 v[8:9], v[8:9], v[28:29]
	v_pk_mul_f32 v[10:11], v[10:11], v[226:227]
	v_pk_mul_f32 v[232:233], v[30:31], v[228:229]
	v_pk_mul_f32 v[32:33], v[6:7], v[6:7] op_sel_hi:[0,1]
	v_pk_mul_f32 v[222:223], v[8:9], v[8:9] op_sel_hi:[0,1]
	v_pk_mul_f32 v[30:31], v[10:11], v[232:233]
	s_waitcnt lgkmcnt(0)
	v_mul_f32_e32 v25, v3, v5
	v_pk_mul_f32 v[30:31], v[30:31], v[30:31] op_sel:[0,1] op_sel_hi:[1,0]
	v_mov_b32_e32 v3, v33
	v_mov_b32_e32 v19, v223
	ds_bpermute_b32 v23, v163, v30
	v_pk_mul_f32 v[2:3], v[2:3], v[18:19]
	v_mul_f32_e32 v6, v195, v5
	ds_bpermute_b32 v21, v163, v3
	v_cndmask_b32_e64 v225, v195, v6, s[0:1]
	v_mul_f32_e32 v224, v15, v225
	v_mul_f32_e32 v13, v13, v224
	v_mov_b32_e32 v5, v30
	v_mul_f32_e32 v12, v14, v13
	v_pk_mul_f32 v[14:15], v[194:195], v[24:25]
	s_waitcnt lgkmcnt(1)
	v_pk_mul_f32 v[4:5], v[4:5], v[22:23]
	v_mov_b32_e32 v234, v231
	v_mov_b32_e32 v235, v17
	v_mov_b32_e32 v231, v16
	v_pk_mul_f32 v[16:17], v[4:5], v[14:15]
	s_waitcnt lgkmcnt(0)
	v_pk_mul_f32 v[2:3], v[2:3], v[20:21]
	v_mul_f32_e32 v10, v15, v23
	v_pk_mul_f32 v[236:237], v[2:3], v[16:17]
	ds_bpermute_b32 v171, v163, v236
	v_mul_f32_e32 v2, v17, v21
	v_cndmask_b32_e64 v3, v17, v2, s[0:1]
	v_mul_f32_e32 v2, v9, v3
	v_pk_mul_f32 v[16:17], v[28:29], v[2:3]
	v_mul_f32_e32 v3, v8, v2
	s_waitcnt lgkmcnt(0)
	v_mul_f32_e32 v5, v237, v171
	v_mul_f32_e32 v2, v7, v3
	v_cndmask_b32_e64 v7, v237, v5, s[0:1]
	v_mul_f32_e32 v6, v14, v7
	v_mul_f32_e32 v5, v4, v6
	v_pk_mul_f32 v[2:3], v[26:27], v[2:3]
	v_mov_b32_e32 v23, v24
	v_mul_f32_e32 v4, v20, v5
	v_mov_b32_e32 v19, v169
	v_pk_mul_f32 v[234:235], v[234:235], v[224:225]
	v_pk_mul_f32 v[8:9], v[22:23], v[6:7]
	v_pk_mul_f32 v[4:5], v[18:19], v[4:5]
	v_cvt_pk_bf16_f32 v224, v2, v3
	v_cndmask_b32_e64 v3, v15, v10, s[0:1]
	v_cvt_pk_bf16_f32 v222, v4, v5
	v_cvt_pk_bf16_f32 v223, v8, v9
	v_cvt_pk_bf16_f32 v225, v16, v17
	v_mul_f32_e32 v2, v233, v3
	v_mov_b32_e32 v4, v227
	v_mov_b32_e32 v5, v229
	v_mfma_f32_32x32x16_bf16 v[50:65], v[138:141], v[222:225], v[50:65]
	v_mul_f32_e64 v140, v230, v12
	v_mul_f32_e64 v141, v231, v13
	v_mul_f32_e64 v230, v4, v2
	v_mul_f32_e64 v231, v5, v3
	v_mul_f32_e32 v139, v11, v2
	v_mul_f32_e32 v138, v232, v139
	v_mov_b32_e32 v227, v228
	v_pk_mul_f32 v[138:139], v[226:227], v[138:139]
	v_cvt_pk_bf16_f32 v140, v140, v141
	v_mfma_f32_32x32x16_bf16 v[34:49], v[218:221], v[222:225], v[34:49]
	v_cvt_pk_bf16_f32 v138, v138, v139
	v_cvt_pk_bf16_f32 v139, v230, v231
	v_cvt_pk_bf16_f32 v141, v234, v235
	s_nop 1
	v_mfma_f32_32x32x16_bf16 v[50:65], v[130:133], v[138:141], v[50:65]
	v_mul_f32_e32 v130, v236, v171
	v_mul_f32_e32 v131, v130, v237
	v_cmp_gt_f32_e32 vcc, s88, v131
	s_cmp_lg_u64 vcc, exec
	v_mfma_f32_32x32x16_bf16 v[34:49], v[134:137], v[138:141], v[34:49]
	s_cbranch_scc0 .LBB0_548
	s_add_i32 s93, s72, -1
	s_sub_i32 s77, s77, 32
	s_sub_i32 s59, s59, 32
	s_cmp_lt_i32 s93, 2
	s_mov_b32 s94, -1
	v_subrev_u32_e32 v165, 32, v165
	v_add_u32_e32 v167, 0xfffff000, v167
	s_cselect_b64 s[80:81], -1, 0
	s_mov_b64 s[82:83], 0
	s_and_b64 vcc, exec, s[80:81]
	s_cbranch_vccz .LBB0_545
	s_branch .LBB0_549

; __device__ __forceinline__ void attn_phase(LAS unsigned char* lds, const bf16_t* Q, const bf16_t* Kb, const bf16_t* VT, const bf16_t* Zs, bf16_t* OZ, int vcu, int G) {
;     ...
;         int kt = qb; bool done = false;
;     ...
;             ATT_TILE(true)
;             if (__all(carry < STOP)) { done = true; break; }
;         }
;     ...
;             ATT_TILE(false)
;             if (__all(carry < STOP)) break;
.LBB0_549:
	s_nop 7
	s_nop 3
	v_mov_b64_e32 v[2:3], v[34:35]
	v_mov_b64_e32 v[4:5], v[36:37]
	v_mov_b64_e32 v[6:7], v[38:39]
	v_mov_b64_e32 v[8:9], v[40:41]
	v_mov_b64_e32 v[10:11], v[42:43]
	v_mov_b64_e32 v[12:13], v[44:45]
	v_mov_b64_e32 v[14:15], v[46:47]
	v_mov_b64_e32 v[16:17], v[48:49]
	v_mov_b64_e32 v[18:19], v[50:51]
	v_mov_b64_e32 v[20:21], v[52:53]
	v_mov_b64_e32 v[22:23], v[54:55]
	v_mov_b64_e32 v[24:25], v[56:57]
	v_mov_b64_e32 v[26:27], v[58:59]
	v_mov_b64_e32 v[28:29], v[60:61]
	v_mov_b64_e32 v[30:31], v[62:63]
	v_mov_b64_e32 v[32:33], v[64:65]
	s_mov_b64 s[80:81], 0
	s_and_b64 vcc, exec, s[82:83]
	s_cbranch_vccz .LBB0_551
	v_mov_b64_e32 v[18:19], v[50:51]
	s_nop 3
	v_mov_b64_e32 v[2:3], v[34:35]
	s_add_i32 s94, s72, -2
	s_mov_b64 s[80:81], -1
	v_mov_b64_e32 v[20:21], v[52:53]
	v_mov_b64_e32 v[22:23], v[54:55]
	v_mov_b64_e32 v[24:25], v[56:57]
	v_mov_b64_e32 v[26:27], v[58:59]
	v_mov_b64_e32 v[28:29], v[60:61]
	v_mov_b64_e32 v[30:31], v[62:63]
	v_mov_b64_e32 v[32:33], v[64:65]
	v_mov_b64_e32 v[4:5], v[36:37]
	v_mov_b64_e32 v[6:7], v[38:39]
	v_mov_b64_e32 v[8:9], v[40:41]
	v_mov_b64_e32 v[10:11], v[42:43]
	v_mov_b64_e32 v[12:13], v[44:45]
	v_mov_b64_e32 v[14:15], v[46:47]
	v_mov_b64_e32 v[16:17], v[48:49]
	v_mov_b32_e32 v131, v195
